# XCD barrier: non-leaders poll the global generation word directly; L1 invalidate issued with the arrival atomic instead of after release
# speedup vs baseline: 1.0189x; 1.0121x over previous
; __device__ __forceinline__ int otid(int wv) { int t; asm volatile("v_mbcnt_lo_u32_b32 %0, -1, 0\n\tv_mbcnt_hi_u32_b32 %0, -1, %0\n\tv_lshl_add_u32 %0, %1, 6, %0" : "=&v"(t) : "s"(wv)); return t; }
; __device__ __forceinline__ unsigned xb_add(unsigned* p, unsigned v) { return __hip_atomic_fetch_add(p, v, __ATOMIC_RELAXED, __HIP_MEMORY_SCOPE_AGENT); }
; __device__ __forceinline__ unsigned xb_xcc_id() { return (unsigned)__builtin_amdgcn_s_getreg((3 << 11) | 20) & 0xFu; }
; __device__ __forceinline__ void xcd_barrier(const XcdBarrier& b, int wv) {
;     ...
;     if (otid(wv) == 0) {
;         unsigned* bar = b.bar;
;         unsigned bx = (unsigned)__builtin_amdgcn_readfirstlane((int)xb_xcc_id()); asm volatile("" : "+s"(bx));
;         __builtin_amdgcn_s_waitcnt(0);
;         unsigned nloc = b.st[0], nx = b.st[1];
;         if (nloc == 0u) { xcd_barrier_complete(bar, bx, nloc, nx); b.st[0] = nloc; b.st[1] = nx; }
;         const unsigned old = xb_add(&bar[XB_XSUB(bx)], 1u);
.LBB0_140:
	s_mov_b64 s[4:5], exec
	v_mbcnt_lo_u32_b32 v1, s4, 0
	v_mbcnt_hi_u32_b32 v1, s5, v1
	s_lshl_b32 s3, s3, 6
	s_mov_b32 s9, 0
	v_cmp_eq_u32_e32 vcc, 0, v1
	s_and_saveexec_b64 s[6:7], vcc
	s_cbranch_execz .LBB0_142
	s_add_i32 s8, s3, 0x500
	s_lshl_b64 s[8:9], s[8:9], 2
	s_add_u32 s8, s82, s8
	s_addc_u32 s9, s83, s9
	s_bcnt1_i32_b64 s4, s[4:5]
	v_mov_b32_e32 v3, 0
	v_mov_b32_e32 v4, s4
	global_atomic_add v3, v3, v4, s[8:9] sc0
	buffer_inv sc1

; __device__ __forceinline__ unsigned xb_ld(unsigned* p)              { return __hip_atomic_load(p, __ATOMIC_RELAXED, __HIP_MEMORY_SCOPE_AGENT); }
; #define XB_SPIN(cond, bar) do { unsigned _sp = 0; while (cond) { __builtin_amdgcn_s_sleep(1); \
;     if ((++_sp & 255u) == 0u) { if (xb_ld(&(bar)[XB_TMO])) break; if (_sp > XB_SPIN_CAP) { atomicAdd(&(bar)[XB_TMO], 1u); break; } } } } while (0)
; __device__ __forceinline__ void xcd_barrier(const XcdBarrier& b, int wv) {
;     ...
;             XB_SPIN(xb_ld(&bar[XB_XGEN(bx)]) == gen, bar);
;             __builtin_amdgcn_fence(__ATOMIC_ACQUIRE, "agent");
;             asm volatile("s_waitcnt vmcnt(0)" ::: "memory");
.LBB0_155:
	s_or_b64 exec, exec, s[6:7]
	s_waitcnt vmcnt(0)
	s_waitcnt vmcnt(0)

; __device__ __forceinline__ unsigned xb_add(unsigned* p, unsigned v) { return __hip_atomic_fetch_add(p, v, __ATOMIC_RELAXED, __HIP_MEMORY_SCOPE_AGENT); }
; __device__ __forceinline__ void xcd_barrier(const XcdBarrier& b, int wv) {
;     ...
;             __builtin_amdgcn_fence(__ATOMIC_ACQUIRE, "agent");
;             xb_add(&bar[XB_XGEN(bx)], 1u);
.LBB0_173:
	s_or_b64 exec, exec, s[4:5]
	s_mov_b64 s[4:5], exec
	v_mbcnt_lo_u32_b32 v0, s4, 0
	v_mbcnt_hi_u32_b32 v0, s5, v0
	s_mov_b32 s9, 0
	v_cmp_eq_u32_e32 vcc, 0, v0
	s_waitcnt vmcnt(0)
	s_and_saveexec_b64 s[6:7], vcc
	s_cbranch_execz .LBB0_175
	s_add_i32 s8, s3, 0x900
	s_lshl_b64 s[8:9], s[8:9], 2
	s_add_u32 s8, s82, s8
	s_addc_u32 s9, s83, s9
	s_bcnt1_i32_b64 s3, s[4:5]
	v_mov_b32_e32 v0, 0
	v_mov_b32_e32 v1, s3
	global_atomic_add v0, v1, s[8:9]

; __device__ __forceinline__ int otid(int wv) { int t; asm volatile("v_mbcnt_lo_u32_b32 %0, -1, 0\n\tv_mbcnt_hi_u32_b32 %0, -1, %0\n\tv_lshl_add_u32 %0, %1, 6, %0" : "=&v"(t) : "s"(wv)); return t; }
; __device__ __forceinline__ unsigned xb_add(unsigned* p, unsigned v) { return __hip_atomic_fetch_add(p, v, __ATOMIC_RELAXED, __HIP_MEMORY_SCOPE_AGENT); }
; __device__ __forceinline__ unsigned xb_xcc_id() { return (unsigned)__builtin_amdgcn_s_getreg((3 << 11) | 20) & 0xFu; }
; __device__ __forceinline__ void xcd_barrier(const XcdBarrier& b, int wv) {
;     ...
;     if (otid(wv) == 0) {
;         unsigned* bar = b.bar;
;         unsigned bx = (unsigned)__builtin_amdgcn_readfirstlane((int)xb_xcc_id()); asm volatile("" : "+s"(bx));
;         __builtin_amdgcn_s_waitcnt(0);
;         unsigned nloc = b.st[0], nx = b.st[1];
;         if (nloc == 0u) { xcd_barrier_complete(bar, bx, nloc, nx); b.st[0] = nloc; b.st[1] = nx; }
;         const unsigned old = xb_add(&bar[XB_XSUB(bx)], 1u);
.LBB0_241:
	s_mov_b64 s[10:11], exec
	v_mbcnt_lo_u32_b32 v1, s10, 0
	v_mbcnt_hi_u32_b32 v1, s11, v1
	s_lshl_b32 s42, s20, 6
	v_cmp_eq_u32_e32 vcc, 0, v1
	s_and_saveexec_b64 s[14:15], vcc
	s_cbranch_execz .LBB0_243
	s_add_i32 s36, s42, 0x500
	s_lshl_b64 s[16:17], s[36:37], 2
	s_add_u32 s16, s82, s16
	s_addc_u32 s17, s83, s17
	s_bcnt1_i32_b64 s10, s[10:11]
	v_mov_b32_e32 v4, s10
	global_atomic_add v4, v0, v4, s[16:17] sc0
	buffer_inv sc1

; __device__ __forceinline__ unsigned xb_ld(unsigned* p)              { return __hip_atomic_load(p, __ATOMIC_RELAXED, __HIP_MEMORY_SCOPE_AGENT); }
; #define XB_SPIN(cond, bar) do { unsigned _sp = 0; while (cond) { __builtin_amdgcn_s_sleep(1); \
;     if ((++_sp & 255u) == 0u) { if (xb_ld(&(bar)[XB_TMO])) break; if (_sp > XB_SPIN_CAP) { atomicAdd(&(bar)[XB_TMO], 1u); break; } } } } while (0)
; __device__ __forceinline__ void xcd_barrier(const XcdBarrier& b, int wv) {
;     ...
;             XB_SPIN(xb_ld(&bar[XB_XGEN(bx)]) == gen, bar);
;             __builtin_amdgcn_fence(__ATOMIC_ACQUIRE, "agent");
;             asm volatile("s_waitcnt vmcnt(0)" ::: "memory");
.LBB0_256:
	s_or_b64 exec, exec, s[14:15]
	s_waitcnt vmcnt(0)
	s_waitcnt vmcnt(0)

; __device__ __forceinline__ unsigned xb_add(unsigned* p, unsigned v) { return __hip_atomic_fetch_add(p, v, __ATOMIC_RELAXED, __HIP_MEMORY_SCOPE_AGENT); }
; __device__ __forceinline__ void xcd_barrier(const XcdBarrier& b, int wv) {
;     ...
;             __builtin_amdgcn_fence(__ATOMIC_ACQUIRE, "agent");
;             xb_add(&bar[XB_XGEN(bx)], 1u);
.LBB0_274:
	s_or_b64 exec, exec, s[10:11]
	s_mov_b64 s[10:11], exec
	v_mbcnt_lo_u32_b32 v1, s10, 0
	v_mbcnt_hi_u32_b32 v1, s11, v1
	v_cmp_eq_u32_e32 vcc, 0, v1
	s_waitcnt vmcnt(0)
	s_and_saveexec_b64 s[14:15], vcc
	s_cbranch_execz .LBB0_276
	s_add_i32 s36, s42, 0x900
	s_lshl_b64 s[16:17], s[36:37], 2
	s_add_u32 s16, s82, s16
	s_addc_u32 s17, s83, s17
	s_bcnt1_i32_b64 s10, s[10:11]
	v_mov_b32_e32 v1, s10
	global_atomic_add v0, v1, s[16:17]

; __device__ __forceinline__ int otid(int wv) { int t; asm volatile("v_mbcnt_lo_u32_b32 %0, -1, 0\n\tv_mbcnt_hi_u32_b32 %0, -1, %0\n\tv_lshl_add_u32 %0, %1, 6, %0" : "=&v"(t) : "s"(wv)); return t; }
; __device__ __forceinline__ unsigned xb_add(unsigned* p, unsigned v) { return __hip_atomic_fetch_add(p, v, __ATOMIC_RELAXED, __HIP_MEMORY_SCOPE_AGENT); }
; __device__ __forceinline__ unsigned xb_xcc_id() { return (unsigned)__builtin_amdgcn_s_getreg((3 << 11) | 20) & 0xFu; }
; __device__ __forceinline__ void xcd_barrier(const XcdBarrier& b, int wv) {
;     ...
;     if (otid(wv) == 0) {
;         unsigned* bar = b.bar;
;         unsigned bx = (unsigned)__builtin_amdgcn_readfirstlane((int)xb_xcc_id()); asm volatile("" : "+s"(bx));
;         __builtin_amdgcn_s_waitcnt(0);
;         unsigned nloc = b.st[0], nx = b.st[1];
;         if (nloc == 0u) { xcd_barrier_complete(bar, bx, nloc, nx); b.st[0] = nloc; b.st[1] = nx; }
;         const unsigned old = xb_add(&bar[XB_XSUB(bx)], 1u);
.LBB0_349:
	s_mov_b64 s[6:7], exec
	v_mbcnt_lo_u32_b32 v1, s6, 0
	v_mbcnt_hi_u32_b32 v1, s7, v1
	s_lshl_b32 s42, s16, 6
	v_cmp_eq_u32_e32 vcc, 0, v1
	s_and_saveexec_b64 s[10:11], vcc
	s_cbranch_execz .LBB0_351
	s_add_i32 s36, s42, 0x500
	s_lshl_b64 s[14:15], s[36:37], 2
	s_add_u32 s14, s82, s14
	s_addc_u32 s15, s83, s15
	s_bcnt1_i32_b64 s6, s[6:7]
	v_mov_b32_e32 v4, s6
	global_atomic_add v4, v0, v4, s[14:15] sc0
	buffer_inv sc1

; __device__ __forceinline__ unsigned xb_ld(unsigned* p)              { return __hip_atomic_load(p, __ATOMIC_RELAXED, __HIP_MEMORY_SCOPE_AGENT); }
; #define XB_SPIN(cond, bar) do { unsigned _sp = 0; while (cond) { __builtin_amdgcn_s_sleep(1); \
;     if ((++_sp & 255u) == 0u) { if (xb_ld(&(bar)[XB_TMO])) break; if (_sp > XB_SPIN_CAP) { atomicAdd(&(bar)[XB_TMO], 1u); break; } } } } while (0)
; __device__ __forceinline__ void xcd_barrier(const XcdBarrier& b, int wv) {
;     ...
;             XB_SPIN(xb_ld(&bar[XB_XGEN(bx)]) == gen, bar);
;             __builtin_amdgcn_fence(__ATOMIC_ACQUIRE, "agent");
;             asm volatile("s_waitcnt vmcnt(0)" ::: "memory");
.LBB0_364:
	s_or_b64 exec, exec, s[10:11]
	s_waitcnt vmcnt(0)
	s_waitcnt vmcnt(0)

; __device__ __forceinline__ unsigned xb_add(unsigned* p, unsigned v) { return __hip_atomic_fetch_add(p, v, __ATOMIC_RELAXED, __HIP_MEMORY_SCOPE_AGENT); }
; __device__ __forceinline__ void xcd_barrier(const XcdBarrier& b, int wv) {
;     ...
;             __builtin_amdgcn_fence(__ATOMIC_ACQUIRE, "agent");
;             xb_add(&bar[XB_XGEN(bx)], 1u);
.LBB0_382:
	s_or_b64 exec, exec, s[6:7]
	s_mov_b64 s[6:7], exec
	v_mbcnt_lo_u32_b32 v1, s6, 0
	v_mbcnt_hi_u32_b32 v1, s7, v1
	v_cmp_eq_u32_e32 vcc, 0, v1
	s_waitcnt vmcnt(0)
	s_and_saveexec_b64 s[10:11], vcc
	s_cbranch_execz .LBB0_384
	s_add_i32 s36, s42, 0x900
	s_lshl_b64 s[14:15], s[36:37], 2
	s_add_u32 s14, s82, s14
	s_addc_u32 s15, s83, s15
	s_bcnt1_i32_b64 s6, s[6:7]
	v_mov_b32_e32 v1, s6
	global_atomic_add v0, v1, s[14:15]

; __device__ __forceinline__ int otid(int wv) { int t; asm volatile("v_mbcnt_lo_u32_b32 %0, -1, 0\n\tv_mbcnt_hi_u32_b32 %0, -1, %0\n\tv_lshl_add_u32 %0, %1, 6, %0" : "=&v"(t) : "s"(wv)); return t; }
; __device__ __forceinline__ unsigned xb_add(unsigned* p, unsigned v) { return __hip_atomic_fetch_add(p, v, __ATOMIC_RELAXED, __HIP_MEMORY_SCOPE_AGENT); }
; __device__ __forceinline__ unsigned xb_xcc_id() { return (unsigned)__builtin_amdgcn_s_getreg((3 << 11) | 20) & 0xFu; }
; __device__ __forceinline__ void xcd_barrier(const XcdBarrier& b, int wv) {
;     ...
;     if (otid(wv) == 0) {
;         unsigned* bar = b.bar;
;         unsigned bx = (unsigned)__builtin_amdgcn_readfirstlane((int)xb_xcc_id()); asm volatile("" : "+s"(bx));
;         __builtin_amdgcn_s_waitcnt(0);
;         unsigned nloc = b.st[0], nx = b.st[1];
;         if (nloc == 0u) { xcd_barrier_complete(bar, bx, nloc, nx); b.st[0] = nloc; b.st[1] = nx; }
;         const unsigned old = xb_add(&bar[XB_XSUB(bx)], 1u);
.LBB0_523:
	s_mov_b64 s[4:5], exec
	v_mbcnt_lo_u32_b32 v1, s4, 0
	v_mbcnt_hi_u32_b32 v1, s5, v1
	s_lshl_b32 s42, s10, 6
	v_cmp_eq_u32_e32 vcc, 0, v1
	s_and_saveexec_b64 s[6:7], vcc
	s_cbranch_execz .LBB0_525
	s_add_i32 s36, s42, 0x500
	s_lshl_b64 s[8:9], s[36:37], 2
	s_add_u32 s8, s82, s8
	s_addc_u32 s9, s83, s9
	s_bcnt1_i32_b64 s4, s[4:5]
	v_mov_b32_e32 v4, s4
	global_atomic_add v4, v0, v4, s[8:9] sc0
	buffer_inv sc1

; __device__ __forceinline__ unsigned xb_add(unsigned* p, unsigned v) { return __hip_atomic_fetch_add(p, v, __ATOMIC_RELAXED, __HIP_MEMORY_SCOPE_AGENT); }
; __device__ __forceinline__ void xcd_barrier(const XcdBarrier& b, int wv) {
;     ...
;             __builtin_amdgcn_fence(__ATOMIC_ACQUIRE, "agent");
;             xb_add(&bar[XB_XGEN(bx)], 1u);
.LBB0_556:
	s_or_b64 exec, exec, s[4:5]
	s_mov_b64 s[4:5], exec
	v_mbcnt_lo_u32_b32 v1, s4, 0
	v_mbcnt_hi_u32_b32 v1, s5, v1
	v_cmp_eq_u32_e32 vcc, 0, v1
	s_waitcnt vmcnt(0)
	s_and_saveexec_b64 s[6:7], vcc
	s_cbranch_execz .LBB0_558
	s_add_i32 s36, s42, 0x900
	s_lshl_b64 s[8:9], s[36:37], 2
	s_add_u32 s8, s82, s8
	s_addc_u32 s9, s83, s9
	s_bcnt1_i32_b64 s4, s[4:5]
	v_mov_b32_e32 v1, s4
	global_atomic_add v0, v1, s[8:9]

; __device__ __forceinline__ int otid(int wv) { int t; asm volatile("v_mbcnt_lo_u32_b32 %0, -1, 0\n\tv_mbcnt_hi_u32_b32 %0, -1, %0\n\tv_lshl_add_u32 %0, %1, 6, %0" : "=&v"(t) : "s"(wv)); return t; }
; __device__ __forceinline__ unsigned xb_add(unsigned* p, unsigned v) { return __hip_atomic_fetch_add(p, v, __ATOMIC_RELAXED, __HIP_MEMORY_SCOPE_AGENT); }
; __device__ __forceinline__ unsigned xb_xcc_id() { return (unsigned)__builtin_amdgcn_s_getreg((3 << 11) | 20) & 0xFu; }
; __device__ __forceinline__ void xcd_barrier(const XcdBarrier& b, int wv) {
;     ...
;     if (otid(wv) == 0) {
;         unsigned* bar = b.bar;
;         unsigned bx = (unsigned)__builtin_amdgcn_readfirstlane((int)xb_xcc_id()); asm volatile("" : "+s"(bx));
;         __builtin_amdgcn_s_waitcnt(0);
;         unsigned nloc = b.st[0], nx = b.st[1];
;         if (nloc == 0u) { xcd_barrier_complete(bar, bx, nloc, nx); b.st[0] = nloc; b.st[1] = nx; }
;         const unsigned old = xb_add(&bar[XB_XSUB(bx)], 1u);
.LBB0_762:
	s_mov_b64 s[4:5], exec
	v_mbcnt_lo_u32_b32 v1, s4, 0
	v_mbcnt_hi_u32_b32 v1, s5, v1
	s_lshl_b32 s42, s12, 6
	v_cmp_eq_u32_e32 vcc, 0, v1
	s_and_saveexec_b64 s[6:7], vcc
	s_cbranch_execz .LBB0_764
	s_add_i32 s36, s42, 0x500
	s_lshl_b64 s[8:9], s[36:37], 2
	s_add_u32 s8, s82, s8
	s_addc_u32 s9, s83, s9
	s_bcnt1_i32_b64 s4, s[4:5]
	v_mov_b32_e32 v4, s4
	global_atomic_add v4, v0, v4, s[8:9] sc0
	buffer_inv sc1

; __device__ __forceinline__ unsigned xb_add(unsigned* p, unsigned v) { return __hip_atomic_fetch_add(p, v, __ATOMIC_RELAXED, __HIP_MEMORY_SCOPE_AGENT); }
; __device__ __forceinline__ void xcd_barrier(const XcdBarrier& b, int wv) {
;     ...
;             __builtin_amdgcn_fence(__ATOMIC_ACQUIRE, "agent");
;             xb_add(&bar[XB_XGEN(bx)], 1u);
.LBB0_795:
	s_or_b64 exec, exec, s[4:5]
	s_mov_b64 s[4:5], exec
	v_mbcnt_lo_u32_b32 v1, s4, 0
	v_mbcnt_hi_u32_b32 v1, s5, v1
	v_cmp_eq_u32_e32 vcc, 0, v1
	s_waitcnt vmcnt(0)
	s_and_saveexec_b64 s[6:7], vcc
	s_cbranch_execz .LBB0_444
	s_add_i32 s36, s42, 0x900
	s_lshl_b64 s[8:9], s[36:37], 2
	s_add_u32 s8, s82, s8
	s_addc_u32 s9, s83, s9
	s_bcnt1_i32_b64 s4, s[4:5]
	v_mov_b32_e32 v1, s4
	global_atomic_add v0, v1, s[8:9]
	s_branch .LBB0_444

; __device__ __forceinline__ int otid(int wv) { int t; asm volatile("v_mbcnt_lo_u32_b32 %0, -1, 0\n\tv_mbcnt_hi_u32_b32 %0, -1, %0\n\tv_lshl_add_u32 %0, %1, 6, %0" : "=&v"(t) : "s"(wv)); return t; }
; __device__ __forceinline__ unsigned xb_add(unsigned* p, unsigned v) { return __hip_atomic_fetch_add(p, v, __ATOMIC_RELAXED, __HIP_MEMORY_SCOPE_AGENT); }
; __device__ __forceinline__ unsigned xb_xcc_id() { return (unsigned)__builtin_amdgcn_s_getreg((3 << 11) | 20) & 0xFu; }
; __device__ __forceinline__ void xcd_barrier(const XcdBarrier& b, int wv) {
;     ...
;     if (otid(wv) == 0) {
;         unsigned* bar = b.bar;
;         unsigned bx = (unsigned)__builtin_amdgcn_readfirstlane((int)xb_xcc_id()); asm volatile("" : "+s"(bx));
;         __builtin_amdgcn_s_waitcnt(0);
;         unsigned nloc = b.st[0], nx = b.st[1];
;         if (nloc == 0u) { xcd_barrier_complete(bar, bx, nloc, nx); b.st[0] = nloc; b.st[1] = nx; }
;         const unsigned old = xb_add(&bar[XB_XSUB(bx)], 1u);
.LBB0_816:
	s_mov_b64 s[8:9], exec
	v_mbcnt_lo_u32_b32 v5, s8, 0
	v_mbcnt_hi_u32_b32 v5, s9, v5
	s_lshl_b32 s24, s14, 6
	s_mov_b32 s13, 0
	v_cmp_eq_u32_e32 vcc, 0, v5
	s_and_saveexec_b64 s[10:11], vcc
	s_cbranch_execz .LBB0_818
	s_add_i32 s12, s24, 0x500
	s_lshl_b64 s[12:13], s[12:13], 2
	s_add_u32 s12, s82, s12
	s_addc_u32 s13, s83, s13
	s_bcnt1_i32_b64 s8, s[8:9]
	v_mov_b32_e32 v7, 0
	v_mov_b32_e32 v8, s8
	global_atomic_add v7, v7, v8, s[12:13] sc0
	buffer_inv sc1

; __device__ __forceinline__ unsigned xb_add(unsigned* p, unsigned v) { return __hip_atomic_fetch_add(p, v, __ATOMIC_RELAXED, __HIP_MEMORY_SCOPE_AGENT); }
; __device__ __forceinline__ void xcd_barrier(const XcdBarrier& b, int wv) {
;     ...
;             __builtin_amdgcn_fence(__ATOMIC_ACQUIRE, "agent");
;             xb_add(&bar[XB_XGEN(bx)], 1u);
.LBB0_849:
	s_or_b64 exec, exec, s[8:9]
	s_mov_b64 s[8:9], exec
	v_mbcnt_lo_u32_b32 v4, s8, 0
	v_mbcnt_hi_u32_b32 v4, s9, v4
	s_mov_b32 s13, 0
	v_cmp_eq_u32_e32 vcc, 0, v4
	s_waitcnt vmcnt(0)
	s_and_saveexec_b64 s[10:11], vcc
	s_cbranch_execz .LBB0_851
	s_add_i32 s12, s24, 0x900
	s_lshl_b64 s[12:13], s[12:13], 2
	s_add_u32 s12, s82, s12
	s_addc_u32 s13, s83, s13
	s_bcnt1_i32_b64 s8, s[8:9]
	v_mov_b32_e32 v4, 0
	v_mov_b32_e32 v5, s8
	global_atomic_add v4, v5, s[12:13]
